# baseline (speedup 1.0000x reference)
; __device__ __forceinline__ const float* inp(const Params& p, int i) { auto g = (__attribute__((address_space(1))) const float*)p.in[i]; asm volatile("" : "+s"(g)); return (const float*)g; }
; __device__ __forceinline__ void scan_pc(const Params& p, int j, const u16* R, const u16* K, const u16* V, u16* Y, u16* YB) {
;     ...
;     const float* w0 = inp(p, 8) + (size_t)(j * 2 + d) * CM;
;     const float* a0 = inp(p, 11) + (size_t)(j * 2 + d) * CM;
;     u16* Yw = (ymode == 2) ? YB - (size_t)NPROMPT * CM : Y;
;     int ch = h * 64 + w4 * 16 + fr;
;     unsigned cho = (unsigned)ch * 4u;
;     float w0c = ldo<float>(w0, cho), a0c = ldo<float>(a0, cho), kac = ldo<float>(kap, cho), kkme = ldo<float>(kkp, cho), rkc = ldo<float>(rkp, cho);
;     bf16x8* LB = reinterpret_cast<bf16x8*>(shm + 4 * IMG_ELEMS + 2 * MM_ELEMS) + wv * 256 + lane;
;     if (prod) {
;       _Pragma("unroll") for (int ks = 0; ks < 2; ++ks) { LB[ks * 64] = ldo<bf16x8>(w2T, (unsigned)(ch * 64 + ks * 32 + fq * 8) * 2u); LB[(2 + ks) * 64] = ldo<bf16x8>(a2T, (unsigned)(ch * 64 + ks * 32 + fq * 8) * 2u); }
;     }
.LBB0_2689:
	v_readlane_b32 s68, v248, 36
	v_readlane_b32 s20, v246, 20
	v_readlane_b32 s69, v248, 37
	v_readlane_b32 s21, v246, 21
	s_add_i32 s20, s88, s20
	s_and_b32 s30, s8, 15
	s_mov_b64 s[8:9], s[68:69]
	s_ashr_i32 s21, s20, 31
	s_ashr_i32 s89, s88, 31
	s_lshl_b64 s[20:21], s[20:21], 12
	v_readlane_b32 s74, v248, 42
	v_readlane_b32 s75, v248, 43
	s_add_u32 s8, s8, s20
	s_addc_u32 s9, s9, s21
	s_mov_b64 s[26:27], s[74:75]
	v_lshl_or_b32 v32, s30, 6, v114
	s_add_u32 s20, s26, s20
	v_lshlrev_b32_e32 v33, 2, v32
	s_addc_u32 s21, s27, s21
	global_load_dword v152, v33, s[8:9]
	global_load_dword v153, v33, s[20:21]
	global_load_dword v74, v33, s[46:47]
	global_load_dword v76, v33, s[40:41]
	global_load_dword v78, v33, s[44:45]
	v_readlane_b32 s70, v248, 38
	v_readlane_b32 s71, v248, 39
	v_readlane_b32 s72, v248, 40
	v_readlane_b32 s73, v248, 41
	v_readlane_b32 s76, v248, 44
	v_readlane_b32 s77, v248, 45
	v_readlane_b32 s78, v248, 46
	v_readlane_b32 s79, v248, 47
	v_readlane_b32 s80, v248, 48
	v_readlane_b32 s81, v248, 49
	v_readlane_b32 s82, v248, 50
	v_readlane_b32 s83, v248, 51
	s_mov_b64 s[20:21], exec
	v_readlane_b32 s8, v246, 30
	v_readlane_b32 s9, v246, 31
	s_and_b64 s[8:9], s[20:21], s[8:9]
	s_mov_b64 exec, s[8:9]
	s_cbranch_execz .LBB0_2691
	s_lshl_b64 s[8:9], s[88:89], 17
	v_readlane_b32 s26, v246, 43
	s_add_u32 s26, s26, s8
	v_readlane_b32 s27, v246, 44
	s_addc_u32 s27, s27, s9
	v_readlane_b32 s28, v246, 41
	s_add_u32 s8, s28, s8
	v_readlane_b32 s28, v246, 42
	s_addc_u32 s9, s28, s9
	v_lshl_or_b32 v33, v32, 7, v112
	global_load_dwordx4 v[34:37], v33, s[8:9]
	global_load_dwordx4 v[194:197], v33, s[26:27]
	global_load_dwordx4 v[198:201], v33, s[8:9] offset:64
	global_load_dwordx4 v[202:205], v33, s[26:27] offset:64
	s_waitcnt vmcnt(0)
	ds_write_b128 v111, v[34:37]
	ds_write_b128 v111, v[194:197] offset:2048
	ds_write_b128 v111, v[198:201] offset:1024
	ds_write_b128 v111, v[202:205] offset:3072

; #define STAGE(P, BASE, LD, br, kt) do { \
;     _Pragma("unroll") for (int _i = 0; _i < 2; ++_i) { \
;       const char* _ub = reinterpret_cast<const char*>(BASE) + ((long)((br) + 64 * _i) * (LD) + (long)(kt) * BK) * 2; \
;       __builtin_amdgcn_global_load_lds((const unsigned*)(_ub + ((LD) == lda ? vo_a : vo_b)), \
;         (unsigned*)((char*)(P) + tid_ * 16 + _i * 8192), 16, 0, 0); } } while (0)
; template <class Epi>
; __device__ __forceinline__ void gemm_tile(const u16* __restrict__ A, int lda, const u16* __restrict__ Bt, int ldb,
;                                           int K, int brow, int bcol, const Epi& epi, bool first, bool has_next, int nbrow, int nbcol) {
;   int tid_ = threadIdx.x; asm volatile("" : "+v"(tid_));
;   int wid = tid_ >> 6, lane = tid_ & 63, wr = wid >> 2, wc = wid & 3, fr = lane & 15, fq = lane >> 4;
;   constexpr bool SWAP = Epi::SWAP;
;   unsigned vo_a, vo_b;
;   { int r_, c_; stage_rc(tid_ * 16, r_, c_); vo_a = (unsigned)(r_ * lda + c_) * 2u; vo_b = (unsigned)(r_ * ldb + c_) * 2u; }
;   f32x4 acc[2][2][4][2] = {};
;   bf16x8 At[4][2], B0[2][2], B1[2][2];
;   int nt = K / BK;
;   if (first) {
;     STAGE(SB(0, 0), Bt, ldb, bcol, 0); STAGE(SA(0, 0), A, lda, brow, 0);
;     STAGE(SB(0, 1), Bt, ldb, bcol + HALF, 0); STAGE(SA(0, 1), A, lda, brow + HALF, 0);
.LBB0_2870:
	v_mov_b32_e32 v139, v131
	s_cmp_lg_u32 s3, s92
	s_waitcnt vmcnt(1)
	v_bfe_i32 v1, v139, 27, 1
	v_lshlrev_b32_e32 v144, 4, v139
	v_lshrrev_b32_e32 v1, 22, v1
	v_ashrrev_i32_e32 v0, 31, v139
	v_add_u32_e32 v1, v144, v1
	v_lshrrev_b32_e32 v0, 26, v0
	v_and_b32_e32 v1, 0xfffffc00, v1
	v_add_u32_e32 v0, v139, v0
	v_sub_u32_e32 v1, v144, v1
	v_ashrrev_i32_e32 v0, 6, v0
	v_lshrrev_b32_e32 v2, 4, v1
	v_bitop3_b32 v2, v2, v1, 32 bitop3:0x6c
	v_lshlrev_b32_e32 v1, 3, v0
	v_and_b32_e32 v3, 0x1ffff0, v1
	v_ashrrev_i32_e32 v1, 31, v2
	v_lshrrev_b32_e32 v1, 26, v1
	s_waitcnt vmcnt(1)
	v_add_u32_e32 v4, v2, v1
	v_ashrrev_i32_e32 v1, 6, v4
	v_and_b32_e32 v4, 0xc0, v4
	v_sub_u32_e32 v2, v2, v4
	v_lshlrev_b32_e32 v5, 5, v0
	v_ashrrev_i16_sdwa v2, v182, sext(v2) dst_sel:DWORD dst_unused:UNUSED_PAD src0_sel:DWORD src1_sel:BYTE_0
	v_and_b32_e32 v5, 32, v5
	v_bfe_i32 v2, v2, 0, 16
	v_add_u32_e32 v4, v5, v2
	v_add_lshl_u32 v3, v1, v3, 11
	v_add_u32_e32 v138, 0, v144
	v_lshl_add_u32 v128, v4, 1, v3
	v_add_u32_e32 v137, 0x2000, v138
	v_add_u32_e32 v136, s88, v144
	v_add_u32_e32 v135, 0x4000, v138
	v_add_u32_e32 v134, 0x6000, v138
	s_cbranch_scc1 .LBB0_2872
	s_add_i32 s3, 0, 0x10000
	v_add_u32_e32 v3, s3, v144
	s_ashr_i32 s11, s10, 31
	v_lshl_add_u64 v[4:5], s[0:1], 0, v[128:129]
	s_lshl_b64 s[16:17], s[10:11], 11
	v_readfirstlane_b32 s3, v3
	v_add_u32_e32 v3, 0x2000, v3
	v_lshl_add_u64 v[4:5], v[4:5], 0, s[16:17]
	s_mov_b32 m0, s3
	s_mov_b64 s[18:19], 0x20000
	v_readfirstlane_b32 s3, v3
	global_load_lds_dwordx4 v[4:5], off
	v_lshl_add_u64 v[6:7], v[4:5], 0, s[18:19]
	s_mov_b32 m0, s3
	s_ashr_i32 s13, s12, 31
	global_load_lds_dwordx4 v[6:7], off
	v_lshl_add_u64 v[6:7], s[66:67], 0, v[128:129]
	s_lshl_b64 s[16:17], s[12:13], 11
	v_readfirstlane_b32 s3, v138
	v_lshl_add_u64 v[6:7], v[6:7], 0, s[16:17]
	s_mov_b32 m0, s3
	v_readfirstlane_b32 s3, v137
	global_load_lds_dwordx4 v[6:7], off
	v_lshl_add_u64 v[8:9], v[6:7], 0, s[18:19]
	s_mov_b32 m0, s3
	s_mov_b64 s[16:17], 0x40000
	v_readfirstlane_b32 s3, v136
	v_add_u32_e32 v3, 0x2000, v136
	global_load_lds_dwordx4 v[8:9], off
	v_lshl_add_u64 v[8:9], v[4:5], 0, s[16:17]
	s_mov_b32 m0, s3
	s_mov_b64 s[18:19], 0x60000
	v_readfirstlane_b32 s3, v3
	global_load_lds_dwordx4 v[8:9], off
	v_lshl_add_u64 v[4:5], v[4:5], 0, s[18:19]
	s_mov_b32 m0, s3
	v_readfirstlane_b32 s3, v135
	global_load_lds_dwordx4 v[4:5], off
	v_lshl_add_u64 v[4:5], v[6:7], 0, s[16:17]
	s_mov_b32 m0, s3
	v_readfirstlane_b32 s3, v134
	global_load_lds_dwordx4 v[4:5], off
	v_lshl_add_u64 v[4:5], v[6:7], 0, s[18:19]
	s_mov_b32 m0, s3
	s_nop 0
	global_load_lds_dwordx4 v[4:5], off

; __device__ __forceinline__ unsigned pk2(float a, float b) { f2_t x; x[0] = a; x[1] = b; return __builtin_bit_cast(unsigned, __builtin_convertvector(x, bf2_t)); }
; #define SCHED __builtin_amdgcn_sched_barrier(0)
; template <class Epi>
; __device__ __forceinline__ void gemm_tile(const u16* __restrict__ A, int lda, const u16* __restrict__ Bt, int ldb,
;                                           int K, int brow, int bcol, const Epi& epi, bool first, bool has_next, int nbrow, int nbcol) {
;     ...
;   _Pragma("unroll") for (int ai = 0; ai < 2; ++ai) _Pragma("unroll") for (int bj = 0; bj < 2; ++bj) _Pragma("unroll") for (int m = 0; m < 4; ++m) _Pragma("unroll") for (int n = 0; n < 2; ++n)
;   { if (SWAP) epi.store4(brow + ai * HALF + wr * 64 + m * 16 + fr, bcol + bj * HALF + wc * 32 + n * 16 + fq * 4, acc[ai][bj][m][n]);
;     else epi.store4(brow + ai * HALF + wr * 64 + m * 16 + fq * 4, bcol + bj * HALF + wc * 32 + n * 16 + fr, acc[ai][bj][m][n]); SCHED; }
;   __device__ __forceinline__ void store4(int row, int col, f32x4 v) const {
;     float a0 = fmaxf(v[0], 0.f), a1 = fmaxf(v[1], 0.f), a2 = fmaxf(v[2], 0.f), a3 = fmaxf(v[3], 0.f);
;     uint2 o; o.x = pk2(a0 * a0, a1 * a1); o.y = pk2(a2 * a2, a3 * a3);
;     *reinterpret_cast<uint2*>(hid + (size_t)row * DFF + col) = o;
;   }
.LBB0_2961:
	v_add3_u32 v132, v142, s14, v143
	v_lshlrev_b32_e32 v128, 5, v140
	v_lshlrev_b32_e32 v133, 2, v141
	v_max_f32_e32 v124, 0, v124
	v_max_f32_e32 v125, 0, v125
	v_add3_u32 v134, v128, s12, v133
	v_ashrrev_i32_e32 v133, 31, v132
	v_max_f32_e32 v126, 0, v126
	v_max_f32_e32 v127, 0, v127
	v_pk_mul_f32 v[124:125], v[124:125], v[124:125]
	v_lshlrev_b64 v[136:137], 13, v[132:133]
	v_cvt_pk_bf16_f32 v138, v124, v125
	v_pk_mul_f32 v[124:125], v[126:127], v[126:127]
	v_ashrrev_i32_e32 v135, 31, v134
	v_cvt_pk_bf16_f32 v139, v124, v125
	v_lshl_add_u64 v[126:127], s[58:59], 0, v[136:137]
	v_lshlrev_b64 v[124:125], 1, v[134:135]
	v_lshl_add_u64 v[126:127], v[126:127], 0, v[124:125]
	global_store_dwordx2 v[126:127], v[138:139], off
	v_max_f32_e32 v120, 0, v120
	v_max_f32_e32 v121, 0, v121
	v_max_f32_e32 v122, 0, v122
	v_max_f32_e32 v123, 0, v123
	v_pk_mul_f32 v[120:121], v[120:121], v[120:121]
	v_pk_mul_f32 v[122:123], v[122:123], v[122:123]
	v_cvt_pk_bf16_f32 v120, v120, v121
	v_cvt_pk_bf16_f32 v121, v122, v123
	global_store_dwordx2 v[126:127], v[120:121], off offset:32
	v_add_u32_e32 v120, 16, v132
	v_ashrrev_i32_e32 v121, 31, v120
	v_max_f32_e32 v116, 0, v116
	v_max_f32_e32 v117, 0, v117
	v_max_f32_e32 v118, 0, v118
	v_max_f32_e32 v119, 0, v119
	v_lshlrev_b64 v[120:121], 13, v[120:121]
	v_pk_mul_f32 v[116:117], v[116:117], v[116:117]
	v_pk_mul_f32 v[118:119], v[118:119], v[118:119]
	v_cvt_pk_bf16_f32 v116, v116, v117
	v_cvt_pk_bf16_f32 v117, v118, v119
	v_lshl_add_u64 v[118:119], s[58:59], 0, v[120:121]
	v_lshl_add_u64 v[118:119], v[118:119], 0, v[124:125]
	global_store_dwordx2 v[118:119], v[116:117], off
	v_max_f32_e32 v112, 0, v112
	v_max_f32_e32 v113, 0, v113
	v_max_f32_e32 v114, 0, v114
	v_max_f32_e32 v115, 0, v115
	v_pk_mul_f32 v[112:113], v[112:113], v[112:113]
	v_pk_mul_f32 v[114:115], v[114:115], v[114:115]
	v_cvt_pk_bf16_f32 v112, v112, v113
	v_cvt_pk_bf16_f32 v113, v114, v115
	global_store_dwordx2 v[118:119], v[112:113], off offset:32
	v_add_u32_e32 v112, 32, v132
	v_ashrrev_i32_e32 v113, 31, v112
	v_max_f32_e32 v108, 0, v108
	v_max_f32_e32 v109, 0, v109
	v_max_f32_e32 v110, 0, v110
	v_max_f32_e32 v111, 0, v111
	v_lshlrev_b64 v[112:113], 13, v[112:113]
	v_pk_mul_f32 v[108:109], v[108:109], v[108:109]
	v_pk_mul_f32 v[110:111], v[110:111], v[110:111]
	v_cvt_pk_bf16_f32 v108, v108, v109
	v_cvt_pk_bf16_f32 v109, v110, v111
	v_lshl_add_u64 v[110:111], s[58:59], 0, v[112:113]
	v_lshl_add_u64 v[110:111], v[110:111], 0, v[124:125]
	global_store_dwordx2 v[110:111], v[108:109], off
	v_max_f32_e32 v104, 0, v104
	v_max_f32_e32 v105, 0, v105
	v_max_f32_e32 v106, 0, v106
	v_max_f32_e32 v107, 0, v107
	v_pk_mul_f32 v[104:105], v[104:105], v[104:105]
	v_pk_mul_f32 v[106:107], v[106:107], v[106:107]
	v_cvt_pk_bf16_f32 v104, v104, v105
	v_cvt_pk_bf16_f32 v105, v106, v107
	global_store_dwordx2 v[110:111], v[104:105], off offset:32
	v_add_u32_e32 v104, 48, v132
	v_ashrrev_i32_e32 v105, 31, v104
	v_max_f32_e32 v100, 0, v100
	v_max_f32_e32 v101, 0, v101
	v_max_f32_e32 v102, 0, v102
	v_max_f32_e32 v103, 0, v103
	v_lshlrev_b64 v[104:105], 13, v[104:105]
	v_pk_mul_f32 v[100:101], v[100:101], v[100:101]
	v_pk_mul_f32 v[102:103], v[102:103], v[102:103]
	v_cvt_pk_bf16_f32 v100, v100, v101
	v_cvt_pk_bf16_f32 v101, v102, v103
	v_lshl_add_u64 v[102:103], s[58:59], 0, v[104:105]
	v_lshl_add_u64 v[102:103], v[102:103], 0, v[124:125]
	global_store_dwordx2 v[102:103], v[100:101], off
	v_max_f32_e32 v96, 0, v96
	v_max_f32_e32 v97, 0, v97
	v_max_f32_e32 v98, 0, v98
	v_max_f32_e32 v99, 0, v99
	v_pk_mul_f32 v[96:97], v[96:97], v[96:97]
	v_pk_mul_f32 v[98:99], v[98:99], v[98:99]
	v_cvt_pk_bf16_f32 v96, v96, v97
	v_cvt_pk_bf16_f32 v97, v98, v99
	global_store_dwordx2 v[102:103], v[96:97], off offset:32
	v_max_f32_e32 v92, 0, v92
	v_max_f32_e32 v93, 0, v93
	v_max_f32_e32 v94, 0, v94
	v_max_f32_e32 v95, 0, v95
	v_pk_mul_f32 v[92:93], v[92:93], v[92:93]
	v_pk_mul_f32 v[94:95], v[94:95], v[94:95]
	v_cvt_pk_bf16_f32 v92, v92, v93
	v_cvt_pk_bf16_f32 v93, v94, v95
	global_store_dwordx2 v[126:127], v[92:93], off offset:256
	v_max_f32_e32 v88, 0, v88
	v_max_f32_e32 v89, 0, v89
	v_max_f32_e32 v90, 0, v90
	v_max_f32_e32 v91, 0, v91
	v_pk_mul_f32 v[88:89], v[88:89], v[88:89]
	v_pk_mul_f32 v[90:91], v[90:91], v[90:91]
	v_cvt_pk_bf16_f32 v88, v88, v89
	v_cvt_pk_bf16_f32 v89, v90, v91
	global_store_dwordx2 v[126:127], v[88:89], off offset:288
	v_max_f32_e32 v84, 0, v84
	v_max_f32_e32 v85, 0, v85
	v_max_f32_e32 v86, 0, v86
	v_max_f32_e32 v87, 0, v87
	v_pk_mul_f32 v[84:85], v[84:85], v[84:85]
	v_pk_mul_f32 v[86:87], v[86:87], v[86:87]
	v_cvt_pk_bf16_f32 v84, v84, v85
	v_cvt_pk_bf16_f32 v85, v86, v87
	global_store_dwordx2 v[118:119], v[84:85], off offset:256
	v_max_f32_e32 v80, 0, v80
	v_max_f32_e32 v81, 0, v81
	v_max_f32_e32 v82, 0, v82
	v_max_f32_e32 v83, 0, v83
	v_pk_mul_f32 v[80:81], v[80:81], v[80:81]
	v_pk_mul_f32 v[82:83], v[82:83], v[82:83]
	v_cvt_pk_bf16_f32 v80, v80, v81
	v_cvt_pk_bf16_f32 v81, v82, v83
	global_store_dwordx2 v[118:119], v[80:81], off offset:288
	v_max_f32_e32 v76, 0, v76
	v_max_f32_e32 v77, 0, v77
	v_max_f32_e32 v78, 0, v78
	v_max_f32_e32 v79, 0, v79
	v_pk_mul_f32 v[76:77], v[76:77], v[76:77]
	v_pk_mul_f32 v[78:79], v[78:79], v[78:79]
	v_cvt_pk_bf16_f32 v76, v76, v77
	v_cvt_pk_bf16_f32 v77, v78, v79
	global_store_dwordx2 v[110:111], v[76:77], off offset:256
	v_max_f32_e32 v72, 0, v72
	v_max_f32_e32 v73, 0, v73
	v_max_f32_e32 v74, 0, v74
	v_max_f32_e32 v75, 0, v75
	v_pk_mul_f32 v[72:73], v[72:73], v[72:73]
	v_pk_mul_f32 v[74:75], v[74:75], v[74:75]
	v_cvt_pk_bf16_f32 v72, v72, v73
	v_cvt_pk_bf16_f32 v73, v74, v75
	global_store_dwordx2 v[110:111], v[72:73], off offset:288
; __device__ __forceinline__ unsigned pk2(float a, float b) { f2_t x; x[0] = a; x[1] = b; return __builtin_bit_cast(unsigned, __builtin_convertvector(x, bf2_t)); }
; #define SCHED __builtin_amdgcn_sched_barrier(0)
; template <class Epi>
; __device__ __forceinline__ void gemm_tile(const u16* __restrict__ A, int lda, const u16* __restrict__ Bt, int ldb,
;                                           int K, int brow, int bcol, const Epi& epi, bool first, bool has_next, int nbrow, int nbcol) {
;     ...
;   _Pragma("unroll") for (int ai = 0; ai < 2; ++ai) _Pragma("unroll") for (int bj = 0; bj < 2; ++bj) _Pragma("unroll") for (int m = 0; m < 4; ++m) _Pragma("unroll") for (int n = 0; n < 2; ++n)
;   { if (SWAP) epi.store4(brow + ai * HALF + wr * 64 + m * 16 + fr, bcol + bj * HALF + wc * 32 + n * 16 + fq * 4, acc[ai][bj][m][n]);
;     else epi.store4(brow + ai * HALF + wr * 64 + m * 16 + fq * 4, bcol + bj * HALF + wc * 32 + n * 16 + fr, acc[ai][bj][m][n]); SCHED; }
;   __device__ __forceinline__ void store4(int row, int col, f32x4 v) const {
;     float a0 = fmaxf(v[0], 0.f), a1 = fmaxf(v[1], 0.f), a2 = fmaxf(v[2], 0.f), a3 = fmaxf(v[3], 0.f);
;     uint2 o; o.x = pk2(a0 * a0, a1 * a1); o.y = pk2(a2 * a2, a3 * a3);
;     *reinterpret_cast<uint2*>(hid + (size_t)row * DFF + col) = o;
;   }
	v_max_f32_e32 v68, 0, v68
	v_max_f32_e32 v69, 0, v69
	v_max_f32_e32 v70, 0, v70
	v_max_f32_e32 v71, 0, v71
	v_pk_mul_f32 v[68:69], v[68:69], v[68:69]
	v_pk_mul_f32 v[70:71], v[70:71], v[70:71]
	v_cvt_pk_bf16_f32 v68, v68, v69
	v_cvt_pk_bf16_f32 v69, v70, v71
	global_store_dwordx2 v[102:103], v[68:69], off offset:256
	v_max_f32_e32 v64, 0, v64
	v_max_f32_e32 v65, 0, v65
	v_max_f32_e32 v66, 0, v66
	v_max_f32_e32 v67, 0, v67
	v_pk_mul_f32 v[64:65], v[64:65], v[64:65]
	v_pk_mul_f32 v[66:67], v[66:67], v[66:67]
	v_cvt_pk_bf16_f32 v64, v64, v65
	v_cvt_pk_bf16_f32 v65, v66, v67
	global_store_dwordx2 v[102:103], v[64:65], off offset:288
	v_add_u32_e32 v64, 0x80, v132
	v_ashrrev_i32_e32 v65, 31, v64
	v_max_f32_e32 v60, 0, v60
	v_max_f32_e32 v61, 0, v61
	v_max_f32_e32 v62, 0, v62
	v_max_f32_e32 v63, 0, v63
	v_lshlrev_b64 v[64:65], 13, v[64:65]
	v_pk_mul_f32 v[60:61], v[60:61], v[60:61]
	v_pk_mul_f32 v[62:63], v[62:63], v[62:63]
	v_cvt_pk_bf16_f32 v60, v60, v61
	v_cvt_pk_bf16_f32 v61, v62, v63
	v_lshl_add_u64 v[62:63], s[58:59], 0, v[64:65]
	v_lshl_add_u64 v[62:63], v[62:63], 0, v[124:125]
	global_store_dwordx2 v[62:63], v[60:61], off
	v_max_f32_e32 v56, 0, v56
	v_max_f32_e32 v57, 0, v57
	v_max_f32_e32 v58, 0, v58
	v_max_f32_e32 v59, 0, v59
	v_pk_mul_f32 v[56:57], v[56:57], v[56:57]
	v_pk_mul_f32 v[58:59], v[58:59], v[58:59]
	v_cvt_pk_bf16_f32 v56, v56, v57
	v_cvt_pk_bf16_f32 v57, v58, v59
	global_store_dwordx2 v[62:63], v[56:57], off offset:32
	v_add_u32_e32 v56, 0x90, v132
	v_ashrrev_i32_e32 v57, 31, v56
	v_max_f32_e32 v52, 0, v52
	v_max_f32_e32 v53, 0, v53
	v_max_f32_e32 v54, 0, v54
	v_max_f32_e32 v55, 0, v55
	v_lshlrev_b64 v[56:57], 13, v[56:57]
	v_pk_mul_f32 v[52:53], v[52:53], v[52:53]
	v_pk_mul_f32 v[54:55], v[54:55], v[54:55]
	v_cvt_pk_bf16_f32 v52, v52, v53
	v_cvt_pk_bf16_f32 v53, v54, v55
	v_lshl_add_u64 v[54:55], s[58:59], 0, v[56:57]
	v_lshl_add_u64 v[54:55], v[54:55], 0, v[124:125]
	global_store_dwordx2 v[54:55], v[52:53], off
	v_max_f32_e32 v48, 0, v48
	v_max_f32_e32 v49, 0, v49
	v_max_f32_e32 v50, 0, v50
	v_max_f32_e32 v51, 0, v51
	v_pk_mul_f32 v[48:49], v[48:49], v[48:49]
	v_pk_mul_f32 v[50:51], v[50:51], v[50:51]
	v_cvt_pk_bf16_f32 v48, v48, v49
	v_cvt_pk_bf16_f32 v49, v50, v51
	global_store_dwordx2 v[54:55], v[48:49], off offset:32
	v_add_u32_e32 v48, 0xa0, v132
	v_ashrrev_i32_e32 v49, 31, v48
	v_max_f32_e32 v44, 0, v44
	v_max_f32_e32 v45, 0, v45
	v_max_f32_e32 v46, 0, v46
	v_max_f32_e32 v47, 0, v47
	v_lshlrev_b64 v[48:49], 13, v[48:49]
	v_pk_mul_f32 v[44:45], v[44:45], v[44:45]
	v_pk_mul_f32 v[46:47], v[46:47], v[46:47]
	v_cvt_pk_bf16_f32 v44, v44, v45
	v_cvt_pk_bf16_f32 v45, v46, v47
	v_lshl_add_u64 v[46:47], s[58:59], 0, v[48:49]
	v_lshl_add_u64 v[46:47], v[46:47], 0, v[124:125]
	global_store_dwordx2 v[46:47], v[44:45], off
	v_max_f32_e32 v40, 0, v40
	v_max_f32_e32 v41, 0, v41
	v_max_f32_e32 v42, 0, v42
	v_max_f32_e32 v43, 0, v43
	v_pk_mul_f32 v[40:41], v[40:41], v[40:41]
	v_pk_mul_f32 v[42:43], v[42:43], v[42:43]
	v_cvt_pk_bf16_f32 v40, v40, v41
	v_cvt_pk_bf16_f32 v41, v42, v43
	global_store_dwordx2 v[46:47], v[40:41], off offset:32
	v_add_u32_e32 v40, 0xb0, v132
	v_ashrrev_i32_e32 v41, 31, v40
	v_max_f32_e32 v36, 0, v36
	v_max_f32_e32 v37, 0, v37
	v_max_f32_e32 v38, 0, v38
	v_max_f32_e32 v39, 0, v39
	v_lshlrev_b64 v[40:41], 13, v[40:41]
	v_pk_mul_f32 v[36:37], v[36:37], v[36:37]
	v_pk_mul_f32 v[38:39], v[38:39], v[38:39]
	v_cvt_pk_bf16_f32 v36, v36, v37
	v_cvt_pk_bf16_f32 v37, v38, v39
	v_lshl_add_u64 v[38:39], s[58:59], 0, v[40:41]
	v_lshl_add_u64 v[38:39], v[38:39], 0, v[124:125]
	global_store_dwordx2 v[38:39], v[36:37], off
	v_max_f32_e32 v32, 0, v32
	v_max_f32_e32 v33, 0, v33
	v_max_f32_e32 v34, 0, v34
	v_max_f32_e32 v35, 0, v35
	v_pk_mul_f32 v[32:33], v[32:33], v[32:33]
	v_pk_mul_f32 v[34:35], v[34:35], v[34:35]
	v_cvt_pk_bf16_f32 v32, v32, v33
	v_cvt_pk_bf16_f32 v33, v34, v35
	global_store_dwordx2 v[38:39], v[32:33], off offset:32
	v_max_f32_e32 v28, 0, v28
	v_max_f32_e32 v29, 0, v29
	v_max_f32_e32 v30, 0, v30
	v_max_f32_e32 v31, 0, v31
	v_pk_mul_f32 v[28:29], v[28:29], v[28:29]
	v_pk_mul_f32 v[30:31], v[30:31], v[30:31]
	v_cvt_pk_bf16_f32 v28, v28, v29
	v_cvt_pk_bf16_f32 v29, v30, v31
	global_store_dwordx2 v[62:63], v[28:29], off offset:256
	v_max_f32_e32 v24, 0, v24
	v_max_f32_e32 v25, 0, v25
	v_max_f32_e32 v26, 0, v26
	v_max_f32_e32 v27, 0, v27
	v_pk_mul_f32 v[24:25], v[24:25], v[24:25]
	v_pk_mul_f32 v[26:27], v[26:27], v[26:27]
	v_cvt_pk_bf16_f32 v24, v24, v25
	v_cvt_pk_bf16_f32 v25, v26, v27
	global_store_dwordx2 v[62:63], v[24:25], off offset:288
	v_max_f32_e32 v20, 0, v20
	v_max_f32_e32 v21, 0, v21
	v_max_f32_e32 v22, 0, v22
	v_max_f32_e32 v23, 0, v23
	v_pk_mul_f32 v[20:21], v[20:21], v[20:21]
	v_pk_mul_f32 v[22:23], v[22:23], v[22:23]
	v_cvt_pk_bf16_f32 v20, v20, v21
	v_cvt_pk_bf16_f32 v21, v22, v23
	global_store_dwordx2 v[54:55], v[20:21], off offset:256
	v_max_f32_e32 v16, 0, v16
	v_max_f32_e32 v17, 0, v17
	v_max_f32_e32 v18, 0, v18
	v_max_f32_e32 v19, 0, v19
	v_pk_mul_f32 v[16:17], v[16:17], v[16:17]
	v_pk_mul_f32 v[18:19], v[18:19], v[18:19]
	v_cvt_pk_bf16_f32 v16, v16, v17
	v_cvt_pk_bf16_f32 v17, v18, v19
	global_store_dwordx2 v[54:55], v[16:17], off offset:288
	v_max_f32_e32 v12, 0, v12
	v_max_f32_e32 v13, 0, v13
	v_max_f32_e32 v14, 0, v14
	v_max_f32_e32 v15, 0, v15
	v_pk_mul_f32 v[12:13], v[12:13], v[12:13]
	v_pk_mul_f32 v[14:15], v[14:15], v[14:15]
	v_cvt_pk_bf16_f32 v12, v12, v13
	v_cvt_pk_bf16_f32 v13, v14, v15
	global_store_dwordx2 v[46:47], v[12:13], off offset:256
	v_max_f32_e32 v8, 0, v8
	v_max_f32_e32 v9, 0, v9
	v_max_f32_e32 v10, 0, v10
	v_max_f32_e32 v11, 0, v11
	v_pk_mul_f32 v[8:9], v[8:9], v[8:9]
	v_pk_mul_f32 v[10:11], v[10:11], v[10:11]
	v_cvt_pk_bf16_f32 v8, v8, v9
	v_cvt_pk_bf16_f32 v9, v10, v11
	global_store_dwordx2 v[46:47], v[8:9], off offset:288
	v_max_f32_e32 v4, 0, v4
	v_max_f32_e32 v5, 0, v5
	v_max_f32_e32 v6, 0, v6
	v_max_f32_e32 v7, 0, v7
	v_pk_mul_f32 v[4:5], v[4:5], v[4:5]
	v_pk_mul_f32 v[6:7], v[6:7], v[6:7]
	v_cvt_pk_bf16_f32 v4, v4, v5
	v_cvt_pk_bf16_f32 v5, v6, v7
	global_store_dwordx2 v[38:39], v[4:5], off offset:256
	v_max_f32_e32 v0, 0, v0
	v_max_f32_e32 v1, 0, v1
	v_max_f32_e32 v2, 0, v2
	v_max_f32_e32 v3, 0, v3
	v_pk_mul_f32 v[0:1], v[0:1], v[0:1]
	v_pk_mul_f32 v[2:3], v[2:3], v[2:3]
	v_cvt_pk_bf16_f32 v0, v0, v1
	v_cvt_pk_bf16_f32 v1, v2, v3
	global_store_dwordx2 v[38:39], v[0:1], off offset:288
	s_andn2_b64 vcc, exec, s[6:7]
	s_mov_b32 s9, s2
	s_mov_b32 s12, s8
	s_mov_b32 s14, s10
	s_cbranch_vccz .LBB0_2978

; __device__ __forceinline__ unsigned pk2(float a, float b) { f2_t x; x[0] = a; x[1] = b; return __builtin_bit_cast(unsigned, __builtin_convertvector(x, bf2_t)); }
; #define SCHED __builtin_amdgcn_sched_barrier(0)
; template <class Epi>
; __device__ __forceinline__ void gemm_tile(const u16* __restrict__ A, int lda, const u16* __restrict__ Bt, int ldb,
;                                           int K, int brow, int bcol, const Epi& epi, bool first, bool has_next, int nbrow, int nbcol) {
;     ...
;   _Pragma("unroll") for (int ai = 0; ai < 2; ++ai) _Pragma("unroll") for (int bj = 0; bj < 2; ++bj) _Pragma("unroll") for (int m = 0; m < 4; ++m) _Pragma("unroll") for (int n = 0; n < 2; ++n)
;   { if (SWAP) epi.store4(brow + ai * HALF + wr * 64 + m * 16 + fr, bcol + bj * HALF + wc * 32 + n * 16 + fq * 4, acc[ai][bj][m][n]);
;     else epi.store4(brow + ai * HALF + wr * 64 + m * 16 + fq * 4, bcol + bj * HALF + wc * 32 + n * 16 + fr, acc[ai][bj][m][n]); SCHED; }
;   __device__ __forceinline__ void store4(int row, int col, f32x4 v) const {
;     float a0 = fmaxf(v[0], 0.f), a1 = fmaxf(v[1], 0.f), a2 = fmaxf(v[2], 0.f), a3 = fmaxf(v[3], 0.f);
;     uint2 o; o.x = pk2(a0 * a0, a1 * a1); o.y = pk2(a2 * a2, a3 * a3);
;     *reinterpret_cast<uint2*>(hid + (size_t)row * DFF + col) = o;
;   }
.LBB0_3040:
	v_add3_u32 v132, v142, s20, v143
	v_lshlrev_b32_e32 v128, 5, v140
	v_lshlrev_b32_e32 v133, 2, v141
	v_max_f32_e32 v124, 0, v124
	v_max_f32_e32 v125, 0, v125
	v_add3_u32 v134, v128, s18, v133
	v_ashrrev_i32_e32 v133, 31, v132
	v_max_f32_e32 v126, 0, v126
	v_max_f32_e32 v127, 0, v127
	v_pk_mul_f32 v[124:125], v[124:125], v[124:125]
	v_lshlrev_b64 v[136:137], 13, v[132:133]
	v_cvt_pk_bf16_f32 v138, v124, v125
	v_pk_mul_f32 v[124:125], v[126:127], v[126:127]
	v_ashrrev_i32_e32 v135, 31, v134
	v_cvt_pk_bf16_f32 v139, v124, v125
	v_lshl_add_u64 v[126:127], s[8:9], 0, v[136:137]
	v_lshlrev_b64 v[124:125], 1, v[134:135]
	v_lshl_add_u64 v[126:127], v[126:127], 0, v[124:125]
	flat_store_dwordx2 v[126:127], v[138:139]
	v_max_f32_e32 v120, 0, v120
	v_max_f32_e32 v121, 0, v121
	v_max_f32_e32 v122, 0, v122
	v_max_f32_e32 v123, 0, v123
	v_pk_mul_f32 v[120:121], v[120:121], v[120:121]
	v_pk_mul_f32 v[122:123], v[122:123], v[122:123]
	v_cvt_pk_bf16_f32 v120, v120, v121
	v_cvt_pk_bf16_f32 v121, v122, v123
	flat_store_dwordx2 v[126:127], v[120:121] offset:32
	v_add_u32_e32 v120, 16, v132
	v_ashrrev_i32_e32 v121, 31, v120
	v_max_f32_e32 v116, 0, v116
	v_max_f32_e32 v117, 0, v117
	v_max_f32_e32 v118, 0, v118
	v_max_f32_e32 v119, 0, v119
	v_lshlrev_b64 v[120:121], 13, v[120:121]
	v_pk_mul_f32 v[116:117], v[116:117], v[116:117]
	v_pk_mul_f32 v[118:119], v[118:119], v[118:119]
	v_cvt_pk_bf16_f32 v116, v116, v117
	v_cvt_pk_bf16_f32 v117, v118, v119
	v_lshl_add_u64 v[118:119], s[8:9], 0, v[120:121]
	v_lshl_add_u64 v[118:119], v[118:119], 0, v[124:125]
	flat_store_dwordx2 v[118:119], v[116:117]
	v_max_f32_e32 v112, 0, v112
	v_max_f32_e32 v113, 0, v113
	v_max_f32_e32 v114, 0, v114
	v_max_f32_e32 v115, 0, v115
	v_pk_mul_f32 v[112:113], v[112:113], v[112:113]
	v_pk_mul_f32 v[114:115], v[114:115], v[114:115]
	v_cvt_pk_bf16_f32 v112, v112, v113
	v_cvt_pk_bf16_f32 v113, v114, v115
	flat_store_dwordx2 v[118:119], v[112:113] offset:32
	v_add_u32_e32 v112, 32, v132
	v_ashrrev_i32_e32 v113, 31, v112
	v_max_f32_e32 v108, 0, v108
	v_max_f32_e32 v109, 0, v109
	v_max_f32_e32 v110, 0, v110
	v_max_f32_e32 v111, 0, v111
	v_lshlrev_b64 v[112:113], 13, v[112:113]
	v_pk_mul_f32 v[108:109], v[108:109], v[108:109]
	v_pk_mul_f32 v[110:111], v[110:111], v[110:111]
	v_cvt_pk_bf16_f32 v108, v108, v109
	v_cvt_pk_bf16_f32 v109, v110, v111
	v_lshl_add_u64 v[110:111], s[8:9], 0, v[112:113]
	v_lshl_add_u64 v[110:111], v[110:111], 0, v[124:125]
	flat_store_dwordx2 v[110:111], v[108:109]
	v_max_f32_e32 v104, 0, v104
	v_max_f32_e32 v105, 0, v105
	v_max_f32_e32 v106, 0, v106
	v_max_f32_e32 v107, 0, v107
	v_pk_mul_f32 v[104:105], v[104:105], v[104:105]
	v_pk_mul_f32 v[106:107], v[106:107], v[106:107]
	v_cvt_pk_bf16_f32 v104, v104, v105
	v_cvt_pk_bf16_f32 v105, v106, v107
	flat_store_dwordx2 v[110:111], v[104:105] offset:32
	v_add_u32_e32 v104, 48, v132
	v_ashrrev_i32_e32 v105, 31, v104
	v_max_f32_e32 v100, 0, v100
	v_max_f32_e32 v101, 0, v101
	v_max_f32_e32 v102, 0, v102
	v_max_f32_e32 v103, 0, v103
	v_lshlrev_b64 v[104:105], 13, v[104:105]
	v_pk_mul_f32 v[100:101], v[100:101], v[100:101]
	v_pk_mul_f32 v[102:103], v[102:103], v[102:103]
	v_cvt_pk_bf16_f32 v100, v100, v101
	v_cvt_pk_bf16_f32 v101, v102, v103
	v_lshl_add_u64 v[102:103], s[8:9], 0, v[104:105]
	v_lshl_add_u64 v[102:103], v[102:103], 0, v[124:125]
	flat_store_dwordx2 v[102:103], v[100:101]
	v_max_f32_e32 v96, 0, v96
	v_max_f32_e32 v97, 0, v97
	v_max_f32_e32 v98, 0, v98
	v_max_f32_e32 v99, 0, v99
	v_pk_mul_f32 v[96:97], v[96:97], v[96:97]
	v_pk_mul_f32 v[98:99], v[98:99], v[98:99]
	v_cvt_pk_bf16_f32 v96, v96, v97
	v_cvt_pk_bf16_f32 v97, v98, v99
	flat_store_dwordx2 v[102:103], v[96:97] offset:32
	v_max_f32_e32 v92, 0, v92
	v_max_f32_e32 v93, 0, v93
	v_max_f32_e32 v94, 0, v94
	v_max_f32_e32 v95, 0, v95
	v_pk_mul_f32 v[92:93], v[92:93], v[92:93]
	v_pk_mul_f32 v[94:95], v[94:95], v[94:95]
	v_cvt_pk_bf16_f32 v92, v92, v93
	v_cvt_pk_bf16_f32 v93, v94, v95
	flat_store_dwordx2 v[126:127], v[92:93] offset:256
	v_max_f32_e32 v88, 0, v88
	v_max_f32_e32 v89, 0, v89
	v_max_f32_e32 v90, 0, v90
	v_max_f32_e32 v91, 0, v91
	v_pk_mul_f32 v[88:89], v[88:89], v[88:89]
	v_pk_mul_f32 v[90:91], v[90:91], v[90:91]
	v_cvt_pk_bf16_f32 v88, v88, v89
	v_cvt_pk_bf16_f32 v89, v90, v91
	flat_store_dwordx2 v[126:127], v[88:89] offset:288
	v_max_f32_e32 v84, 0, v84
	v_max_f32_e32 v85, 0, v85
	v_max_f32_e32 v86, 0, v86
	v_max_f32_e32 v87, 0, v87
	v_pk_mul_f32 v[84:85], v[84:85], v[84:85]
	v_pk_mul_f32 v[86:87], v[86:87], v[86:87]
	v_cvt_pk_bf16_f32 v84, v84, v85
	v_cvt_pk_bf16_f32 v85, v86, v87
	flat_store_dwordx2 v[118:119], v[84:85] offset:256
	v_max_f32_e32 v80, 0, v80
	v_max_f32_e32 v81, 0, v81
	v_max_f32_e32 v82, 0, v82
	v_max_f32_e32 v83, 0, v83
	v_pk_mul_f32 v[80:81], v[80:81], v[80:81]
	v_pk_mul_f32 v[82:83], v[82:83], v[82:83]
	v_cvt_pk_bf16_f32 v80, v80, v81
	v_cvt_pk_bf16_f32 v81, v82, v83
	flat_store_dwordx2 v[118:119], v[80:81] offset:288
	v_max_f32_e32 v76, 0, v76
	v_max_f32_e32 v77, 0, v77
	v_max_f32_e32 v78, 0, v78
	v_max_f32_e32 v79, 0, v79
	v_pk_mul_f32 v[76:77], v[76:77], v[76:77]
	v_pk_mul_f32 v[78:79], v[78:79], v[78:79]
	v_cvt_pk_bf16_f32 v76, v76, v77
	v_cvt_pk_bf16_f32 v77, v78, v79
	flat_store_dwordx2 v[110:111], v[76:77] offset:256
	v_max_f32_e32 v72, 0, v72
	v_max_f32_e32 v73, 0, v73
	v_max_f32_e32 v74, 0, v74
	v_max_f32_e32 v75, 0, v75
	v_pk_mul_f32 v[72:73], v[72:73], v[72:73]
	v_pk_mul_f32 v[74:75], v[74:75], v[74:75]
	v_cvt_pk_bf16_f32 v72, v72, v73
	v_cvt_pk_bf16_f32 v73, v74, v75
	flat_store_dwordx2 v[110:111], v[72:73] offset:288
	v_max_f32_e32 v68, 0, v68
	v_max_f32_e32 v69, 0, v69
	v_max_f32_e32 v70, 0, v70
; __device__ __forceinline__ unsigned pk2(float a, float b) { f2_t x; x[0] = a; x[1] = b; return __builtin_bit_cast(unsigned, __builtin_convertvector(x, bf2_t)); }
; #define SCHED __builtin_amdgcn_sched_barrier(0)
; template <class Epi>
; __device__ __forceinline__ void gemm_tile(const u16* __restrict__ A, int lda, const u16* __restrict__ Bt, int ldb,
;                                           int K, int brow, int bcol, const Epi& epi, bool first, bool has_next, int nbrow, int nbcol) {
;     ...
;   _Pragma("unroll") for (int ai = 0; ai < 2; ++ai) _Pragma("unroll") for (int bj = 0; bj < 2; ++bj) _Pragma("unroll") for (int m = 0; m < 4; ++m) _Pragma("unroll") for (int n = 0; n < 2; ++n)
;   { if (SWAP) epi.store4(brow + ai * HALF + wr * 64 + m * 16 + fr, bcol + bj * HALF + wc * 32 + n * 16 + fq * 4, acc[ai][bj][m][n]);
;     else epi.store4(brow + ai * HALF + wr * 64 + m * 16 + fq * 4, bcol + bj * HALF + wc * 32 + n * 16 + fr, acc[ai][bj][m][n]); SCHED; }
;   __device__ __forceinline__ void store4(int row, int col, f32x4 v) const {
;     float a0 = fmaxf(v[0], 0.f), a1 = fmaxf(v[1], 0.f), a2 = fmaxf(v[2], 0.f), a3 = fmaxf(v[3], 0.f);
;     uint2 o; o.x = pk2(a0 * a0, a1 * a1); o.y = pk2(a2 * a2, a3 * a3);
;     *reinterpret_cast<uint2*>(hid + (size_t)row * DFF + col) = o;
;   }
	v_max_f32_e32 v71, 0, v71
	v_pk_mul_f32 v[68:69], v[68:69], v[68:69]
	v_pk_mul_f32 v[70:71], v[70:71], v[70:71]
	v_cvt_pk_bf16_f32 v68, v68, v69
	v_cvt_pk_bf16_f32 v69, v70, v71
	flat_store_dwordx2 v[102:103], v[68:69] offset:256
	v_max_f32_e32 v64, 0, v64
	v_max_f32_e32 v65, 0, v65
	v_max_f32_e32 v66, 0, v66
	v_max_f32_e32 v67, 0, v67
	v_pk_mul_f32 v[64:65], v[64:65], v[64:65]
	v_pk_mul_f32 v[66:67], v[66:67], v[66:67]
	v_cvt_pk_bf16_f32 v64, v64, v65
	v_cvt_pk_bf16_f32 v65, v66, v67
	flat_store_dwordx2 v[102:103], v[64:65] offset:288
	v_add_u32_e32 v64, 0x80, v132
	v_ashrrev_i32_e32 v65, 31, v64
	v_max_f32_e32 v60, 0, v60
	v_max_f32_e32 v61, 0, v61
	v_max_f32_e32 v62, 0, v62
	v_max_f32_e32 v63, 0, v63
	v_lshlrev_b64 v[64:65], 13, v[64:65]
	v_pk_mul_f32 v[60:61], v[60:61], v[60:61]
	v_pk_mul_f32 v[62:63], v[62:63], v[62:63]
	v_cvt_pk_bf16_f32 v60, v60, v61
	v_cvt_pk_bf16_f32 v61, v62, v63
	v_lshl_add_u64 v[62:63], s[8:9], 0, v[64:65]
	v_lshl_add_u64 v[62:63], v[62:63], 0, v[124:125]
	flat_store_dwordx2 v[62:63], v[60:61]
	v_max_f32_e32 v56, 0, v56
	v_max_f32_e32 v57, 0, v57
	v_max_f32_e32 v58, 0, v58
	v_max_f32_e32 v59, 0, v59
	v_pk_mul_f32 v[56:57], v[56:57], v[56:57]
	v_pk_mul_f32 v[58:59], v[58:59], v[58:59]
	v_cvt_pk_bf16_f32 v56, v56, v57
	v_cvt_pk_bf16_f32 v57, v58, v59
	flat_store_dwordx2 v[62:63], v[56:57] offset:32
	v_add_u32_e32 v56, 0x90, v132
	v_ashrrev_i32_e32 v57, 31, v56
	v_max_f32_e32 v52, 0, v52
	v_max_f32_e32 v53, 0, v53
	v_max_f32_e32 v54, 0, v54
	v_max_f32_e32 v55, 0, v55
	v_lshlrev_b64 v[56:57], 13, v[56:57]
	v_pk_mul_f32 v[52:53], v[52:53], v[52:53]
	v_pk_mul_f32 v[54:55], v[54:55], v[54:55]
	v_cvt_pk_bf16_f32 v52, v52, v53
	v_cvt_pk_bf16_f32 v53, v54, v55
	v_lshl_add_u64 v[54:55], s[8:9], 0, v[56:57]
	v_lshl_add_u64 v[54:55], v[54:55], 0, v[124:125]
	flat_store_dwordx2 v[54:55], v[52:53]
	v_max_f32_e32 v48, 0, v48
	v_max_f32_e32 v49, 0, v49
	v_max_f32_e32 v50, 0, v50
	v_max_f32_e32 v51, 0, v51
	v_pk_mul_f32 v[48:49], v[48:49], v[48:49]
	v_pk_mul_f32 v[50:51], v[50:51], v[50:51]
	v_cvt_pk_bf16_f32 v48, v48, v49
	v_cvt_pk_bf16_f32 v49, v50, v51
	flat_store_dwordx2 v[54:55], v[48:49] offset:32
	v_add_u32_e32 v48, 0xa0, v132
	v_ashrrev_i32_e32 v49, 31, v48
	v_max_f32_e32 v44, 0, v44
	v_max_f32_e32 v45, 0, v45
	v_max_f32_e32 v46, 0, v46
	v_max_f32_e32 v47, 0, v47
	v_lshlrev_b64 v[48:49], 13, v[48:49]
	v_pk_mul_f32 v[44:45], v[44:45], v[44:45]
	v_pk_mul_f32 v[46:47], v[46:47], v[46:47]
	v_cvt_pk_bf16_f32 v44, v44, v45
	v_cvt_pk_bf16_f32 v45, v46, v47
	v_lshl_add_u64 v[46:47], s[8:9], 0, v[48:49]
	v_lshl_add_u64 v[46:47], v[46:47], 0, v[124:125]
	flat_store_dwordx2 v[46:47], v[44:45]
	v_max_f32_e32 v40, 0, v40
	v_max_f32_e32 v41, 0, v41
	v_max_f32_e32 v42, 0, v42
	v_max_f32_e32 v43, 0, v43
	v_pk_mul_f32 v[40:41], v[40:41], v[40:41]
	v_pk_mul_f32 v[42:43], v[42:43], v[42:43]
	v_cvt_pk_bf16_f32 v40, v40, v41
	v_cvt_pk_bf16_f32 v41, v42, v43
	flat_store_dwordx2 v[46:47], v[40:41] offset:32
	v_add_u32_e32 v40, 0xb0, v132
	v_ashrrev_i32_e32 v41, 31, v40
	v_max_f32_e32 v36, 0, v36
	v_max_f32_e32 v37, 0, v37
	v_max_f32_e32 v38, 0, v38
	v_max_f32_e32 v39, 0, v39
	v_lshlrev_b64 v[40:41], 13, v[40:41]
	v_pk_mul_f32 v[36:37], v[36:37], v[36:37]
	v_pk_mul_f32 v[38:39], v[38:39], v[38:39]
	v_cvt_pk_bf16_f32 v36, v36, v37
	v_cvt_pk_bf16_f32 v37, v38, v39
	v_lshl_add_u64 v[38:39], s[8:9], 0, v[40:41]
	v_lshl_add_u64 v[38:39], v[38:39], 0, v[124:125]
	flat_store_dwordx2 v[38:39], v[36:37]
	v_max_f32_e32 v32, 0, v32
	v_max_f32_e32 v33, 0, v33
	v_max_f32_e32 v34, 0, v34
	v_max_f32_e32 v35, 0, v35
	v_pk_mul_f32 v[32:33], v[32:33], v[32:33]
	v_pk_mul_f32 v[34:35], v[34:35], v[34:35]
	v_cvt_pk_bf16_f32 v32, v32, v33
	v_cvt_pk_bf16_f32 v33, v34, v35
	flat_store_dwordx2 v[38:39], v[32:33] offset:32
	v_max_f32_e32 v28, 0, v28
	v_max_f32_e32 v29, 0, v29
	v_max_f32_e32 v30, 0, v30
	v_max_f32_e32 v31, 0, v31
	v_pk_mul_f32 v[28:29], v[28:29], v[28:29]
	v_pk_mul_f32 v[30:31], v[30:31], v[30:31]
	v_cvt_pk_bf16_f32 v28, v28, v29
	v_cvt_pk_bf16_f32 v29, v30, v31
	flat_store_dwordx2 v[62:63], v[28:29] offset:256
	v_max_f32_e32 v24, 0, v24
	v_max_f32_e32 v25, 0, v25
	v_max_f32_e32 v26, 0, v26
	v_max_f32_e32 v27, 0, v27
	v_pk_mul_f32 v[24:25], v[24:25], v[24:25]
	v_pk_mul_f32 v[26:27], v[26:27], v[26:27]
	v_cvt_pk_bf16_f32 v24, v24, v25
	v_cvt_pk_bf16_f32 v25, v26, v27
	flat_store_dwordx2 v[62:63], v[24:25] offset:288
	v_max_f32_e32 v20, 0, v20
	v_max_f32_e32 v21, 0, v21
	v_max_f32_e32 v22, 0, v22
	v_max_f32_e32 v23, 0, v23
	v_pk_mul_f32 v[20:21], v[20:21], v[20:21]
	v_pk_mul_f32 v[22:23], v[22:23], v[22:23]
	v_cvt_pk_bf16_f32 v20, v20, v21
	v_cvt_pk_bf16_f32 v21, v22, v23
	flat_store_dwordx2 v[54:55], v[20:21] offset:256
	v_max_f32_e32 v16, 0, v16
	v_max_f32_e32 v17, 0, v17
	v_max_f32_e32 v18, 0, v18
	v_max_f32_e32 v19, 0, v19
	v_pk_mul_f32 v[16:17], v[16:17], v[16:17]
	v_pk_mul_f32 v[18:19], v[18:19], v[18:19]
	v_cvt_pk_bf16_f32 v16, v16, v17
	v_cvt_pk_bf16_f32 v17, v18, v19
	flat_store_dwordx2 v[54:55], v[16:17] offset:288
	v_max_f32_e32 v12, 0, v12
	v_max_f32_e32 v13, 0, v13
	v_max_f32_e32 v14, 0, v14
	v_max_f32_e32 v15, 0, v15
	v_pk_mul_f32 v[12:13], v[12:13], v[12:13]
	v_pk_mul_f32 v[14:15], v[14:15], v[14:15]
	v_cvt_pk_bf16_f32 v12, v12, v13
	v_cvt_pk_bf16_f32 v13, v14, v15
	flat_store_dwordx2 v[46:47], v[12:13] offset:256
	v_max_f32_e32 v8, 0, v8
	v_max_f32_e32 v9, 0, v9
	v_max_f32_e32 v10, 0, v10
	v_max_f32_e32 v11, 0, v11
	v_pk_mul_f32 v[8:9], v[8:9], v[8:9]
	v_pk_mul_f32 v[10:11], v[10:11], v[10:11]
	v_cvt_pk_bf16_f32 v8, v8, v9
	v_cvt_pk_bf16_f32 v9, v10, v11
	flat_store_dwordx2 v[46:47], v[8:9] offset:288
	v_max_f32_e32 v4, 0, v4
	v_max_f32_e32 v5, 0, v5
	v_max_f32_e32 v6, 0, v6
	v_max_f32_e32 v7, 0, v7
	v_pk_mul_f32 v[4:5], v[4:5], v[4:5]
	v_pk_mul_f32 v[6:7], v[6:7], v[6:7]
	v_cvt_pk_bf16_f32 v4, v4, v5
	v_cvt_pk_bf16_f32 v5, v6, v7
	flat_store_dwordx2 v[38:39], v[4:5] offset:256
	v_max_f32_e32 v0, 0, v0
	v_max_f32_e32 v1, 0, v1
	v_max_f32_e32 v2, 0, v2
	v_max_f32_e32 v3, 0, v3
	v_pk_mul_f32 v[0:1], v[0:1], v[0:1]
	v_pk_mul_f32 v[2:3], v[2:3], v[2:3]
	v_cvt_pk_bf16_f32 v0, v0, v1
	v_cvt_pk_bf16_f32 v1, v2, v3
	flat_store_dwordx2 v[38:39], v[0:1] offset:288
	s_andn2_b64 vcc, exec, s[12:13]
	s_mov_b32 s92, s81
	s_mov_b32 s18, s14
	s_mov_b32 s20, s16
	s_mov_b32 s81, s83
	s_cbranch_vccz .LBB0_3057
